# on top of the single-XCD group-barrier shortcut: combine / FFN-up epilogue stores back to write-back (no sc1)
# baseline (speedup 1.0000x reference)
;     __device__ __forceinline__ void operator()(f32x4 (&acc)[2][2][4][2], const Unit& u, int wr, int wc, int fr, int fq) const {
;     ...
; #pragma unroll
;         for (int bj = 0; bj < 2; ++bj)
; #pragma unroll
;             for (int n = 0; n < 2; ++n) {
;                 const int col = bj * DFF + J0 + n * 4;
;                 const float csc = bj ? 0.6931471805599453f : 1.4426950408889634f;
;                 const f32x4 k0 = *(const f32x4*)(cw + col) * csc, k1 = *(const f32x4*)(cw + 2 * DFF + col) * csc, k2 = *(const f32x4*)(cw + 4 * DFF + col) * csc, kb = *(const f32x4*)(cb + col) * csc;
;                 const f32x4 a0 = acc[0][bj][0][n], a1 = acc[0][bj][1][n], a2 = acc[0][bj][2][n], a3 = acc[0][bj][3][n];
;                 const f32x4 b0 = acc[1][bj][0][n], b1 = acc[1][bj][1][n], b2 = acc[1][bj][2][n], b3 = acc[1][bj][3][n];
;                 f32x4 pa, pb, na, nb;
; #pragma unroll
;                 for (int j = 0; j < 4; ++j) {
;                     const float t = dpp_f<0x121>(a3[j]);
;                     const float s1 = dpp_f<0x111>(b3[j]);
;                     const float un = dpp_f<0x12F>(b0[j]);
;                     const float s0 = dpp_f<0x101>(a0[j]);
;                     pa[j] = t; pb[j] = f0 ? t : s1; na[j] = f15 ? un : s0; nb[j] = un; }
.LBB0_807:
	s_or_b64 exec, exec, s[12:13]
	v_lshlrev_b64 v[166:167], 2, v[148:149]
	v_lshl_add_u64 v[128:129], s[22:23], 0, v[166:167]
	v_lshl_add_u64 v[132:133], s[26:27], 0, v[166:167]
	v_lshl_add_u64 v[162:163], s[36:37], 0, v[166:167]
	v_lshl_add_u64 v[166:167], s[24:25], 0, v[166:167]
	v_mov_b32_dpp v172, v116 row_ror:1 row_mask:0xf bank_mask:0xf bound_ctrl:1
	v_mov_b32_dpp v161, v108 row_shr:1 row_mask:0xf bank_mask:0xf bound_ctrl:1
	v_mov_b32_dpp v174, v112 row_ror:15 row_mask:0xf bank_mask:0xf bound_ctrl:1
	v_mov_b32_dpp v181, v84 row_shl:1 row_mask:0xf bank_mask:0xf bound_ctrl:1
	v_mov_b32_dpp v173, v117 row_ror:1 row_mask:0xf bank_mask:0xf bound_ctrl:1
	v_mov_b32_dpp v183, v109 row_shr:1 row_mask:0xf bank_mask:0xf bound_ctrl:1
	v_mov_b32_dpp v175, v113 row_ror:15 row_mask:0xf bank_mask:0xf bound_ctrl:1
	v_mov_b32_dpp v184, v85 row_shl:1 row_mask:0xf bank_mask:0xf bound_ctrl:1
	v_mov_b32_dpp v176, v118 row_ror:1 row_mask:0xf bank_mask:0xf bound_ctrl:1
	v_mov_b32_dpp v185, v110 row_shr:1 row_mask:0xf bank_mask:0xf bound_ctrl:1
	v_mov_b32_dpp v177, v119 row_ror:1 row_mask:0xf bank_mask:0xf bound_ctrl:1
	v_mov_b32_dpp v187, v111 row_shr:1 row_mask:0xf bank_mask:0xf bound_ctrl:1
	v_mov_b32_dpp v179, v115 row_ror:15 row_mask:0xf bank_mask:0xf bound_ctrl:1
	v_mov_b32_dpp v188, v87 row_shl:1 row_mask:0xf bank_mask:0xf bound_ctrl:1
	v_cndmask_b32_e64 v180, v161, v172, s[8:9]
	v_cndmask_b32_e64 v182, v181, v174, s[4:5]
	v_cndmask_b32_e64 v181, v183, v173, s[8:9]
	v_cndmask_b32_e64 v183, v184, v175, s[4:5]
	v_cndmask_b32_e64 v184, v185, v176, s[8:9]
	v_cndmask_b32_e64 v185, v187, v177, s[8:9]
	v_cndmask_b32_e64 v187, v188, v179, s[4:5]
	v_mov_b32_dpp v178, v114 row_ror:15 row_mask:0xf bank_mask:0xf bound_ctrl:1
	v_mov_b32_dpp v186, v86 row_shl:1 row_mask:0xf bank_mask:0xf bound_ctrl:1
	v_cndmask_b32_e64 v186, v186, v178, s[4:5]
	v_mov_b32_dpp v161, v68 row_shr:1 row_mask:0xf bank_mask:0xf bound_ctrl:1
	s_waitcnt vmcnt(8)
	v_pk_mul_f32 v[128:129], v[224:225], s[40:41] op_sel_hi:[1,0]
	v_pk_mul_f32 v[130:131], v[226:227], s[40:41] op_sel_hi:[1,0]
	v_pk_mul_f32 v[166:167], v[228:229], s[40:41] op_sel_hi:[1,0]
	v_pk_mul_f32 v[168:169], v[230:231], s[40:41] op_sel_hi:[1,0]
	v_pk_mul_f32 v[132:133], v[232:233], s[40:41] op_sel_hi:[1,0]
	v_pk_fma_f32 v[172:173], v[128:129], v[172:173], v[166:167]
	v_pk_mul_f32 v[134:135], v[234:235], s[40:41] op_sel_hi:[1,0]
	v_pk_mul_f32 v[162:163], v[236:237], s[40:41] op_sel_hi:[1,0]
	v_pk_fma_f32 v[176:177], v[130:131], v[176:177], v[168:169]
	v_pk_fma_f32 v[188:189], v[84:85], v[128:129], v[166:167]
	v_pk_fma_f32 v[190:191], v[86:87], v[130:131], v[168:169]
	v_pk_fma_f32 v[192:193], v[124:125], v[128:129], v[166:167]
	v_pk_fma_f32 v[194:195], v[126:127], v[130:131], v[168:169]
	v_pk_fma_f32 v[196:197], v[120:121], v[128:129], v[166:167]
	v_pk_fma_f32 v[198:199], v[122:123], v[130:131], v[168:169]
	v_pk_fma_f32 v[180:181], v[128:129], v[180:181], v[166:167]
	v_pk_fma_f32 v[184:185], v[130:131], v[184:185], v[168:169]
	v_pk_fma_f32 v[200:201], v[112:113], v[128:129], v[166:167]
	v_pk_fma_f32 v[202:203], v[114:115], v[130:131], v[168:169]
	v_pk_fma_f32 v[204:205], v[104:105], v[128:129], v[166:167]
	v_pk_fma_f32 v[206:207], v[106:107], v[130:131], v[168:169]
	v_pk_fma_f32 v[166:167], v[100:101], v[128:129], v[166:167]
	v_pk_fma_f32 v[128:129], v[102:103], v[130:131], v[168:169]
	v_pk_fma_f32 v[84:85], v[84:85], v[132:133], v[172:173]
	v_pk_fma_f32 v[86:87], v[86:87], v[134:135], v[176:177]
	v_pk_fma_f32 v[168:169], v[126:127], v[134:135], v[190:191]
	v_pk_fma_f32 v[172:173], v[124:125], v[132:133], v[188:189]
	v_pk_fma_f32 v[176:177], v[122:123], v[134:135], v[194:195]
	v_pk_fma_f32 v[188:189], v[120:121], v[132:133], v[192:193]
	v_pk_fma_f32 v[190:191], v[118:119], v[134:135], v[198:199]
	v_pk_fma_f32 v[192:193], v[116:117], v[132:133], v[196:197]
	v_pk_fma_f32 v[114:115], v[114:115], v[134:135], v[184:185]
	v_pk_fma_f32 v[112:113], v[112:113], v[132:133], v[180:181]
	v_pk_fma_f32 v[180:181], v[106:107], v[134:135], v[202:203]
	v_pk_fma_f32 v[184:185], v[104:105], v[132:133], v[200:201]
	v_pk_fma_f32 v[194:195], v[102:103], v[134:135], v[206:207]
	v_pk_fma_f32 v[196:197], v[100:101], v[132:133], v[204:205]
	v_pk_fma_f32 v[134:135], v[110:111], v[134:135], v[128:129]
	v_pk_fma_f32 v[128:129], v[124:125], v[162:163], v[84:85]
	v_pk_fma_f32 v[84:85], v[108:109], v[132:133], v[166:167]
	v_or_b32_e32 v132, 4, v150
	v_pk_mul_f32 v[164:165], v[238:239], s[40:41] op_sel_hi:[1,0]
	v_ashrrev_i32_e32 v133, 31, v132
	v_lshlrev_b64 v[166:167], 2, v[148:149]
	v_pk_fma_f32 v[130:131], v[126:127], v[164:165], v[86:87]
	v_pk_fma_f32 v[124:125], v[120:121], v[162:163], v[172:173]
	v_pk_fma_f32 v[126:127], v[122:123], v[164:165], v[168:169]
	v_pk_fma_f32 v[120:121], v[116:117], v[162:163], v[188:189]
	v_pk_fma_f32 v[122:123], v[118:119], v[164:165], v[176:177]
	v_pk_fma_f32 v[116:117], v[162:163], v[182:183], v[192:193]
	v_pk_fma_f32 v[118:119], v[164:165], v[186:187], v[190:191]
	v_pk_fma_f32 v[112:113], v[104:105], v[162:163], v[112:113]
	v_pk_fma_f32 v[114:115], v[106:107], v[164:165], v[114:115]
	v_pk_fma_f32 v[104:105], v[100:101], v[162:163], v[184:185]
	v_pk_fma_f32 v[106:107], v[102:103], v[164:165], v[180:181]
	v_pk_fma_f32 v[100:101], v[108:109], v[162:163], v[196:197]
	v_pk_fma_f32 v[102:103], v[110:111], v[164:165], v[194:195]
	v_pk_fma_f32 v[84:85], v[162:163], v[174:175], v[84:85]
	v_pk_fma_f32 v[86:87], v[164:165], v[178:179], v[134:135]
	v_lshl_add_u64 v[108:109], s[22:23], 0, v[166:167]
	v_lshlrev_b64 v[162:163], 2, v[132:133]
	v_lshl_add_u64 v[166:167], s[24:25], 0, v[166:167]
	global_load_dwordx4 v[224:227], v254, s[22:23]
;     __device__ __forceinline__ void operator()(f32x4 (&acc)[2][2][4][2], const Unit& u, int wr, int wc, int fr, int fq) const {
;     ...
;             for (int n = 0; n < 2; ++n) {
;                 const int col = bj * DFF + J0 + n * 4;
;                 const float csc = bj ? 0.6931471805599453f : 1.4426950408889634f;
;                 const f32x4 k0 = *(const f32x4*)(cw + col) * csc, k1 = *(const f32x4*)(cw + 2 * DFF + col) * csc, k2 = *(const f32x4*)(cw + 4 * DFF + col) * csc, kb = *(const f32x4*)(cb + col) * csc;
;                 const f32x4 a0 = acc[0][bj][0][n], a1 = acc[0][bj][1][n], a2 = acc[0][bj][2][n], a3 = acc[0][bj][3][n];
;                 const f32x4 b0 = acc[1][bj][0][n], b1 = acc[1][bj][1][n], b2 = acc[1][bj][2][n], b3 = acc[1][bj][3][n];
;                 f32x4 pa, pb, na, nb;
; #pragma unroll
;                 for (int j = 0; j < 4; ++j) {
;                     const float t = dpp_f<0x121>(a3[j]);
;                     const float s1 = dpp_f<0x111>(b3[j]);
;                     const float un = dpp_f<0x12F>(b0[j]);
;                     const float s0 = dpp_f<0x101>(a0[j]);
;                     pa[j] = t; pb[j] = f0 ? t : s1; na[j] = f15 ? un : s0; nb[j] = un; }
;                 f32x4 o0 = k2 * a1 + (k1 * a0 + (k0 * pa + kb)), o1 = k2 * a2 + (k1 * a1 + (k0 * a0 + kb)), o2 = k2 * a3 + (k1 * a2 + (k0 * a1 + kb)), o3 = k2 * na + (k1 * a3 + (k0 * a2 + kb));
;                 f32x4 q0 = k2 * b1 + (k1 * b0 + (k0 * pb + kb)), q1 = k2 * b2 + (k1 * b1 + (k0 * b0 + kb)), q2 = k2 * b3 + (k1 * b2 + (k0 * b1 + kb)), q3 = k2 * nb + (k1 * b3 + (k0 * b2 + kb));
;                 asm volatile("" : "+v"(o0), "+v"(o1), "+v"(o2), "+v"(o3), "+v"(q0), "+v"(q1), "+v"(q2), "+v"(q3));
;                 acc[0][bj][0][n] = o0; acc[0][bj][1][n] = o1; acc[0][bj][2][n] = o2; acc[0][bj][3][n] = o3;
;                 acc[1][bj][0][n] = q0; acc[1][bj][1][n] = q1; acc[1][bj][2][n] = q2; acc[1][bj][3][n] = q3;
	v_lshl_add_u64 v[132:133], s[26:27], 0, v[162:163]
	global_load_dwordx4 v[228:231], v254, s[24:25]
	v_lshl_add_u64 v[162:163], s[36:37], 0, v[162:163]
	global_load_dwordx4 v[232:235], v254, s[26:27]
	v_mov_b32_dpp v174, v88 row_ror:15 row_mask:0xf bank_mask:0xf bound_ctrl:1
	global_load_dwordx4 v[236:239], v254, s[36:37]
	v_mov_b32_dpp v181, v76 row_shl:1 row_mask:0xf bank_mask:0xf bound_ctrl:1
	v_mov_b32_dpp v173, v93 row_ror:1 row_mask:0xf bank_mask:0xf bound_ctrl:1
	v_mov_b32_dpp v183, v69 row_shr:1 row_mask:0xf bank_mask:0xf bound_ctrl:1
	v_mov_b32_dpp v175, v89 row_ror:15 row_mask:0xf bank_mask:0xf bound_ctrl:1
	v_mov_b32_dpp v184, v77 row_shl:1 row_mask:0xf bank_mask:0xf bound_ctrl:1
	v_mov_b32_dpp v176, v94 row_ror:1 row_mask:0xf bank_mask:0xf bound_ctrl:1
	v_mov_b32_dpp v185, v70 row_shr:1 row_mask:0xf bank_mask:0xf bound_ctrl:1
	v_mov_b32_dpp v177, v95 row_ror:1 row_mask:0xf bank_mask:0xf bound_ctrl:1
	v_mov_b32_dpp v187, v71 row_shr:1 row_mask:0xf bank_mask:0xf bound_ctrl:1
	v_mov_b32_dpp v179, v91 row_ror:15 row_mask:0xf bank_mask:0xf bound_ctrl:1
	v_mov_b32_dpp v188, v79 row_shl:1 row_mask:0xf bank_mask:0xf bound_ctrl:1
	v_mov_b32_dpp v172, v92 row_ror:1 row_mask:0xf bank_mask:0xf bound_ctrl:1
	v_cndmask_b32_e64 v182, v181, v174, s[4:5]
	v_cndmask_b32_e64 v181, v183, v173, s[8:9]
	v_cndmask_b32_e64 v183, v184, v175, s[4:5]
	v_cndmask_b32_e64 v184, v185, v176, s[8:9]
	v_cndmask_b32_e64 v185, v187, v177, s[8:9]
	v_cndmask_b32_e64 v187, v188, v179, s[4:5]
	v_cndmask_b32_e64 v180, v161, v172, s[8:9]
	v_mov_b32_dpp v186, v78 row_shl:1 row_mask:0xf bank_mask:0xf bound_ctrl:1
	v_mov_b32_dpp v178, v90 row_ror:15 row_mask:0xf bank_mask:0xf bound_ctrl:1
	v_lshlrev_b64 v[150:151], 2, v[150:151]
	v_cndmask_b32_e64 v186, v186, v178, s[4:5]
	v_mov_b32_dpp v161, v32 row_shr:1 row_mask:0xf bank_mask:0xf bound_ctrl:1
	s_waitcnt vmcnt(4)
	v_pk_mul_f32 v[188:189], v[210:211], s[40:41] op_sel_hi:[1,0]
	v_pk_mul_f32 v[190:191], v[208:209], s[40:41] op_sel_hi:[1,0]
	v_pk_mul_f32 v[168:169], v[214:215], s[40:41] op_sel_hi:[1,0]
	v_pk_mul_f32 v[166:167], v[212:213], s[40:41] op_sel_hi:[1,0]
	v_pk_mul_f32 v[192:193], v[218:219], s[40:41] op_sel_hi:[1,0]
	v_pk_mul_f32 v[194:195], v[216:217], s[40:41] op_sel_hi:[1,0]
	v_pk_fma_f32 v[108:109], v[190:191], v[172:173], v[166:167]
	v_pk_fma_f32 v[110:111], v[188:189], v[176:177], v[168:169]
	v_pk_mul_f32 v[164:165], v[222:223], s[40:41] op_sel_hi:[1,0]
	v_pk_mul_f32 v[162:163], v[220:221], s[40:41] op_sel_hi:[1,0]
	v_pk_fma_f32 v[132:133], v[76:77], v[190:191], v[166:167]
	v_pk_fma_f32 v[134:135], v[78:79], v[188:189], v[168:169]
	v_pk_fma_f32 v[180:181], v[190:191], v[180:181], v[166:167]
	v_pk_fma_f32 v[184:185], v[188:189], v[184:185], v[168:169]
	v_pk_fma_f32 v[200:201], v[88:89], v[190:191], v[166:167]
	v_pk_fma_f32 v[202:203], v[90:91], v[188:189], v[168:169]
	v_pk_fma_f32 v[78:79], v[78:79], v[192:193], v[110:111]
	v_pk_fma_f32 v[76:77], v[76:77], v[194:195], v[108:109]
	v_pk_fma_f32 v[172:173], v[72:73], v[190:191], v[166:167]
	v_pk_fma_f32 v[176:177], v[74:75], v[188:189], v[168:169]
	v_pk_fma_f32 v[108:109], v[74:75], v[192:193], v[134:135]
	v_pk_fma_f32 v[204:205], v[72:73], v[194:195], v[132:133]
	v_pk_fma_f32 v[90:91], v[90:91], v[192:193], v[184:185]
	v_pk_fma_f32 v[88:89], v[88:89], v[194:195], v[180:181]
	v_pk_fma_f32 v[180:181], v[82:83], v[192:193], v[202:203]
	v_pk_fma_f32 v[184:185], v[80:81], v[194:195], v[200:201]
	v_pk_fma_f32 v[132:133], v[72:73], v[162:163], v[76:77]
	v_pk_fma_f32 v[134:135], v[74:75], v[164:165], v[78:79]
	v_pk_fma_f32 v[72:73], v[80:81], v[190:191], v[166:167]
	v_pk_fma_f32 v[74:75], v[82:83], v[188:189], v[168:169]
	v_pk_fma_f32 v[196:197], v[96:97], v[190:191], v[166:167]
	v_pk_fma_f32 v[198:199], v[98:99], v[188:189], v[168:169]
	v_pk_fma_f32 v[78:79], v[66:67], v[164:165], v[180:181]
	v_pk_fma_f32 v[76:77], v[64:65], v[162:163], v[184:185]
	v_pk_fma_f32 v[74:75], v[66:67], v[192:193], v[74:75]
	v_pk_fma_f32 v[72:73], v[64:65], v[194:195], v[72:73]
	v_pk_fma_f32 v[64:65], v[64:65], v[190:191], v[166:167]
	v_pk_fma_f32 v[66:67], v[66:67], v[188:189], v[168:169]
	v_pk_fma_f32 v[176:177], v[98:99], v[192:193], v[176:177]
	v_pk_fma_f32 v[172:173], v[96:97], v[194:195], v[172:173]
	v_pk_fma_f32 v[198:199], v[94:95], v[192:193], v[198:199]
	v_pk_fma_f32 v[196:197], v[92:93], v[194:195], v[196:197]
	v_pk_fma_f32 v[66:67], v[70:71], v[192:193], v[66:67]
	v_pk_fma_f32 v[64:65], v[68:69], v[194:195], v[64:65]
	v_lshl_add_u64 v[166:167], v[150:151], 0, s[42:43]
	v_pk_fma_f32 v[110:111], v[98:99], v[164:165], v[108:109]
	v_pk_fma_f32 v[108:109], v[96:97], v[162:163], v[204:205]
	v_pk_fma_f32 v[98:99], v[94:95], v[164:165], v[176:177]
	v_pk_fma_f32 v[96:97], v[92:93], v[162:163], v[172:173]
	v_pk_fma_f32 v[92:93], v[162:163], v[182:183], v[196:197]
	v_pk_fma_f32 v[94:95], v[164:165], v[186:187], v[198:199]
	v_pk_fma_f32 v[90:91], v[82:83], v[164:165], v[90:91]
	v_pk_fma_f32 v[88:89], v[80:81], v[162:163], v[88:89]
	v_pk_fma_f32 v[74:75], v[70:71], v[164:165], v[74:75]
	v_pk_fma_f32 v[72:73], v[68:69], v[162:163], v[72:73]
	v_pk_fma_f32 v[66:67], v[164:165], v[178:179], v[66:67]
	v_pk_fma_f32 v[64:65], v[162:163], v[174:175], v[64:65]
	v_lshl_add_u64 v[68:69], s[22:23], 0, v[166:167]
	v_lshl_add_u64 v[80:81], s[26:27], 0, v[166:167]
	v_lshl_add_u64 v[162:163], s[36:37], 0, v[166:167]
	v_lshl_add_u64 v[166:167], s[24:25], 0, v[166:167]
	global_load_dwordx4 v[208:211], v254, s[22:23] offset:16
	v_mov_b32_dpp v172, v48 row_ror:1 row_mask:0xf bank_mask:0xf bound_ctrl:1
	global_load_dwordx4 v[212:215], v254, s[24:25] offset:16
	v_mov_b32_dpp v174, v44 row_ror:15 row_mask:0xf bank_mask:0xf bound_ctrl:1
;     __device__ __forceinline__ void operator()(f32x4 (&acc)[2][2][4][2], const Unit& u, int wr, int wc, int fr, int fq) const {
;     ...
;             for (int n = 0; n < 2; ++n) {
;                 const int col = bj * DFF + J0 + n * 4;
;                 const float csc = bj ? 0.6931471805599453f : 1.4426950408889634f;
;                 const f32x4 k0 = *(const f32x4*)(cw + col) * csc, k1 = *(const f32x4*)(cw + 2 * DFF + col) * csc, k2 = *(const f32x4*)(cw + 4 * DFF + col) * csc, kb = *(const f32x4*)(cb + col) * csc;
;                 const f32x4 a0 = acc[0][bj][0][n], a1 = acc[0][bj][1][n], a2 = acc[0][bj][2][n], a3 = acc[0][bj][3][n];
;                 const f32x4 b0 = acc[1][bj][0][n], b1 = acc[1][bj][1][n], b2 = acc[1][bj][2][n], b3 = acc[1][bj][3][n];
;                 f32x4 pa, pb, na, nb;
; #pragma unroll
;                 for (int j = 0; j < 4; ++j) {
;                     const float t = dpp_f<0x121>(a3[j]);
;                     const float s1 = dpp_f<0x111>(b3[j]);
;                     const float un = dpp_f<0x12F>(b0[j]);
;                     const float s0 = dpp_f<0x101>(a0[j]);
;                     pa[j] = t; pb[j] = f0 ? t : s1; na[j] = f15 ? un : s0; nb[j] = un; }
;                 f32x4 o0 = k2 * a1 + (k1 * a0 + (k0 * pa + kb)), o1 = k2 * a2 + (k1 * a1 + (k0 * a0 + kb)), o2 = k2 * a3 + (k1 * a2 + (k0 * a1 + kb)), o3 = k2 * na + (k1 * a3 + (k0 * a2 + kb));
;                 f32x4 q0 = k2 * b1 + (k1 * b0 + (k0 * pb + kb)), q1 = k2 * b2 + (k1 * b1 + (k0 * b0 + kb)), q2 = k2 * b3 + (k1 * b2 + (k0 * b1 + kb)), q3 = k2 * nb + (k1 * b3 + (k0 * b2 + kb));
;                 asm volatile("" : "+v"(o0), "+v"(o1), "+v"(o2), "+v"(o3), "+v"(q0), "+v"(q1), "+v"(q2), "+v"(q3));
;                 acc[0][bj][0][n] = o0; acc[0][bj][1][n] = o1; acc[0][bj][2][n] = o2; acc[0][bj][3][n] = o3;
;                 acc[1][bj][0][n] = q0; acc[1][bj][1][n] = q1; acc[1][bj][2][n] = q2; acc[1][bj][3][n] = q3;
	global_load_dwordx4 v[216:219], v254, s[26:27] offset:16
	v_mov_b32_dpp v181, v60 row_shl:1 row_mask:0xf bank_mask:0xf bound_ctrl:1
	global_load_dwordx4 v[220:223], v254, s[36:37] offset:16
	v_mov_b32_dpp v173, v49 row_ror:1 row_mask:0xf bank_mask:0xf bound_ctrl:1
	v_mov_b32_dpp v183, v33 row_shr:1 row_mask:0xf bank_mask:0xf bound_ctrl:1
	v_mov_b32_dpp v175, v45 row_ror:15 row_mask:0xf bank_mask:0xf bound_ctrl:1
	v_mov_b32_dpp v184, v61 row_shl:1 row_mask:0xf bank_mask:0xf bound_ctrl:1
	v_mov_b32_dpp v176, v50 row_ror:1 row_mask:0xf bank_mask:0xf bound_ctrl:1
	v_mov_b32_dpp v185, v34 row_shr:1 row_mask:0xf bank_mask:0xf bound_ctrl:1
	v_mov_b32_dpp v177, v51 row_ror:1 row_mask:0xf bank_mask:0xf bound_ctrl:1
	v_mov_b32_dpp v187, v35 row_shr:1 row_mask:0xf bank_mask:0xf bound_ctrl:1
	v_mov_b32_dpp v179, v47 row_ror:15 row_mask:0xf bank_mask:0xf bound_ctrl:1
	v_mov_b32_dpp v188, v63 row_shl:1 row_mask:0xf bank_mask:0xf bound_ctrl:1
	v_cndmask_b32_e64 v180, v161, v172, s[8:9]
	v_cndmask_b32_e64 v182, v181, v174, s[4:5]
	v_cndmask_b32_e64 v181, v183, v173, s[8:9]
	v_cndmask_b32_e64 v183, v184, v175, s[4:5]
	v_cndmask_b32_e64 v184, v185, v176, s[8:9]
	v_cndmask_b32_e64 v185, v187, v177, s[8:9]
	v_cndmask_b32_e64 v187, v188, v179, s[4:5]
	v_mov_b32_dpp v178, v46 row_ror:15 row_mask:0xf bank_mask:0xf bound_ctrl:1
	v_mov_b32_dpp v186, v62 row_shl:1 row_mask:0xf bank_mask:0xf bound_ctrl:1
	v_cndmask_b32_e64 v186, v186, v178, s[4:5]
	v_lshl_add_u64 v[150:151], v[150:151], 0, s[46:47]
	v_mov_b32_dpp v161, v4 row_shr:1 row_mask:0xf bank_mask:0xf bound_ctrl:1
	s_waitcnt vmcnt(4)
	v_pk_mul_f32 v[188:189], v[226:227], s[44:45] op_sel_hi:[1,0]
	v_pk_mul_f32 v[190:191], v[224:225], s[44:45] op_sel_hi:[1,0]
	v_pk_mul_f32 v[168:169], v[230:231], s[44:45] op_sel_hi:[1,0]
	v_pk_mul_f32 v[166:167], v[228:229], s[44:45] op_sel_hi:[1,0]
	v_pk_mul_f32 v[80:81], v[232:233], s[44:45] op_sel_hi:[1,0]
	v_pk_mul_f32 v[82:83], v[234:235], s[44:45] op_sel_hi:[1,0]
	v_pk_fma_f32 v[68:69], v[190:191], v[172:173], v[166:167]
	v_pk_fma_f32 v[70:71], v[188:189], v[176:177], v[168:169]
	v_pk_fma_f32 v[192:193], v[56:57], v[190:191], v[166:167]
	v_pk_fma_f32 v[194:195], v[58:59], v[188:189], v[168:169]
	v_pk_fma_f32 v[180:181], v[190:191], v[180:181], v[166:167]
	v_pk_fma_f32 v[184:185], v[188:189], v[184:185], v[168:169]
	v_pk_mul_f32 v[164:165], v[238:239], s[44:45] op_sel_hi:[1,0]
	v_pk_mul_f32 v[162:163], v[236:237], s[44:45] op_sel_hi:[1,0]
	v_pk_fma_f32 v[172:173], v[60:61], v[190:191], v[166:167]
	v_pk_fma_f32 v[176:177], v[62:63], v[188:189], v[168:169]
	v_pk_fma_f32 v[196:197], v[52:53], v[190:191], v[166:167]
	v_pk_fma_f32 v[198:199], v[54:55], v[188:189], v[168:169]
	v_pk_fma_f32 v[62:63], v[62:63], v[82:83], v[70:71]
	v_pk_fma_f32 v[60:61], v[60:61], v[80:81], v[68:69]
	v_pk_fma_f32 v[194:195], v[54:55], v[82:83], v[194:195]
	v_pk_fma_f32 v[192:193], v[52:53], v[80:81], v[192:193]
	v_pk_fma_f32 v[184:185], v[46:47], v[82:83], v[184:185]
	v_pk_fma_f32 v[180:181], v[44:45], v[80:81], v[180:181]
	v_pk_fma_f32 v[44:45], v[44:45], v[190:191], v[166:167]
	v_pk_fma_f32 v[46:47], v[46:47], v[188:189], v[168:169]
	v_pk_fma_f32 v[176:177], v[58:59], v[82:83], v[176:177]
	v_pk_fma_f32 v[172:173], v[56:57], v[80:81], v[172:173]
	v_pk_fma_f32 v[198:199], v[50:51], v[82:83], v[198:199]
	v_pk_fma_f32 v[196:197], v[48:49], v[80:81], v[196:197]
	v_pk_fma_f32 v[68:69], v[56:57], v[162:163], v[60:61]
	v_pk_fma_f32 v[70:71], v[58:59], v[164:165], v[62:63]
	v_pk_fma_f32 v[56:57], v[48:49], v[162:163], v[192:193]
	v_pk_fma_f32 v[58:59], v[50:51], v[164:165], v[194:195]
	v_pk_fma_f32 v[48:49], v[40:41], v[162:163], v[180:181]
	v_pk_fma_f32 v[50:51], v[42:43], v[164:165], v[184:185]
	v_pk_fma_f32 v[46:47], v[42:43], v[82:83], v[46:47]
	v_pk_fma_f32 v[44:45], v[40:41], v[80:81], v[44:45]
	v_pk_fma_f32 v[40:41], v[40:41], v[190:191], v[166:167]
	v_pk_fma_f32 v[42:43], v[42:43], v[188:189], v[168:169]
	v_pk_fma_f32 v[44:45], v[36:37], v[162:163], v[44:45]
	v_pk_fma_f32 v[46:47], v[38:39], v[164:165], v[46:47]
	v_pk_fma_f32 v[42:43], v[38:39], v[82:83], v[42:43]
	v_pk_fma_f32 v[40:41], v[36:37], v[80:81], v[40:41]
	v_pk_fma_f32 v[36:37], v[36:37], v[190:191], v[166:167]
	v_pk_fma_f32 v[38:39], v[38:39], v[188:189], v[168:169]
	v_pk_fma_f32 v[40:41], v[32:33], v[162:163], v[40:41]
	v_pk_fma_f32 v[42:43], v[34:35], v[164:165], v[42:43]
	v_pk_fma_f32 v[34:35], v[34:35], v[82:83], v[38:39]
	v_pk_fma_f32 v[32:33], v[32:33], v[80:81], v[36:37]
	v_pk_fma_f32 v[60:61], v[52:53], v[162:163], v[172:173]
	v_pk_fma_f32 v[62:63], v[54:55], v[164:165], v[176:177]
	v_pk_fma_f32 v[52:53], v[162:163], v[182:183], v[196:197]
	v_pk_fma_f32 v[54:55], v[164:165], v[186:187], v[198:199]
	v_pk_fma_f32 v[32:33], v[162:163], v[174:175], v[32:33]
	v_pk_fma_f32 v[34:35], v[164:165], v[178:179], v[34:35]
	v_lshl_add_u64 v[36:37], s[22:23], 0, v[150:151]
	v_lshl_add_u64 v[80:81], s[26:27], 0, v[150:151]
	v_lshl_add_u64 v[162:163], s[36:37], 0, v[150:151]
	v_lshl_add_u64 v[150:151], s[24:25], 0, v[150:151]
	v_mov_b32_dpp v172, v20 row_ror:15 row_mask:0xf bank_mask:0xf bound_ctrl:1
	v_mov_b32_dpp v150, v24 row_ror:1 row_mask:0xf bank_mask:0xf bound_ctrl:1
	v_mov_b32_dpp v151, v25 row_ror:1 row_mask:0xf bank_mask:0xf bound_ctrl:1
	v_mov_b32_dpp v179, v16 row_shl:1 row_mask:0xf bank_mask:0xf bound_ctrl:1
	v_mov_b32_dpp v181, v5 row_shr:1 row_mask:0xf bank_mask:0xf bound_ctrl:1
	v_mov_b32_dpp v182, v17 row_shl:1 row_mask:0xf bank_mask:0xf bound_ctrl:1
	v_cndmask_b32_e64 v178, v161, v150, s[8:9]
	v_cndmask_b32_e64 v180, v179, v172, s[4:5]
	v_cndmask_b32_e64 v179, v181, v151, s[8:9]
	v_mov_b32_dpp v173, v21 row_ror:15 row_mask:0xf bank_mask:0xf bound_ctrl:1
	v_mov_b32_dpp v174, v26 row_ror:1 row_mask:0xf bank_mask:0xf bound_ctrl:1
	v_mov_b32_dpp v183, v6 row_shr:1 row_mask:0xf bank_mask:0xf bound_ctrl:1
	v_mov_b32_dpp v175, v27 row_ror:1 row_mask:0xf bank_mask:0xf bound_ctrl:1
	v_mov_b32_dpp v185, v7 row_shr:1 row_mask:0xf bank_mask:0xf bound_ctrl:1
	v_mov_b32_dpp v177, v23 row_ror:15 row_mask:0xf bank_mask:0xf bound_ctrl:1
	v_mov_b32_dpp v186, v19 row_shl:1 row_mask:0xf bank_mask:0xf bound_ctrl:1
	v_cndmask_b32_e64 v181, v182, v173, s[4:5]
	v_cndmask_b32_e64 v182, v183, v174, s[8:9]
	v_cndmask_b32_e64 v183, v185, v175, s[8:9]
	v_cndmask_b32_e64 v185, v186, v177, s[4:5]
	v_mov_b32_dpp v184, v18 row_shl:1 row_mask:0xf bank_mask:0xf bound_ctrl:1
	v_mov_b32_dpp v176, v22 row_ror:15 row_mask:0xf bank_mask:0xf bound_ctrl:1
	v_cndmask_b32_e64 v184, v184, v176, s[4:5]
	s_waitcnt vmcnt(0)
; __device__ __forceinline__ unsigned cvt_pk_bf16(float lo, float hi) { unsigned r; asm volatile("v_cvt_pk_bf16_f32 %0, %1, %2" : "=v"(r) : "v"(lo), "v"(hi)); return r; }
; #define SG2(gx, vx) (((gx) * (vx)) * __builtin_amdgcn_rcpf(1.0f + __builtin_amdgcn_exp2f(-(gx))))
;     __device__ __forceinline__ void operator()(f32x4 (&acc)[2][2][4][2], const Unit& u, int wr, int wc, int fr, int fq) const {
;     ...
;                 f32x4 o0 = k2 * a1 + (k1 * a0 + (k0 * pa + kb)), o1 = k2 * a2 + (k1 * a1 + (k0 * a0 + kb)), o2 = k2 * a3 + (k1 * a2 + (k0 * a1 + kb)), o3 = k2 * na + (k1 * a3 + (k0 * a2 + kb));
;                 f32x4 q0 = k2 * b1 + (k1 * b0 + (k0 * pb + kb)), q1 = k2 * b2 + (k1 * b1 + (k0 * b0 + kb)), q2 = k2 * b3 + (k1 * b2 + (k0 * b1 + kb)), q3 = k2 * nb + (k1 * b3 + (k0 * b2 + kb));
;                 asm volatile("" : "+v"(o0), "+v"(o1), "+v"(o2), "+v"(o3), "+v"(q0), "+v"(q1), "+v"(q2), "+v"(q3));
;                 acc[0][bj][0][n] = o0; acc[0][bj][1][n] = o1; acc[0][bj][2][n] = o2; acc[0][bj][3][n] = o3;
;                 acc[1][bj][0][n] = q0; acc[1][bj][1][n] = q1; acc[1][bj][2][n] = q2; acc[1][bj][3][n] = q3;
;             }
; #pragma unroll
;         for (int ai = 0; ai < 2; ++ai)
; #pragma unroll
;             for (int m = 0; m < 4; ++m) {
;                 const f32x4 g0 = acc[ai][0][m][0], g1 = acc[ai][0][m][1], v0 = acc[ai][1][m][0], v1 = acc[ai][1][m][1];
;     ...
;                 u32x4 w; w.x = cvt_pk_bf16(SG2(g0[0], v0[0]), SG2(g0[1], v0[1])); w.y = cvt_pk_bf16(SG2(g0[2], v0[2]), SG2(g0[3], v0[3]));
;                 w.z = cvt_pk_bf16(SG2(g1[0], v1[0]), SG2(g1[1], v1[1])); w.w = cvt_pk_bf16(SG2(g1[2], v1[2]), SG2(g1[3], v1[3]));
;     ...
;                 const bool valid = !((ai == 0 && m == 0 && f0) || (ai == 1 && m == 3 && f15));
;                 if (valid) *(u32x4*)(A + (size_t)(sc * 128 + ai * 64 + 4 * fr + m) * DFF + J0) = w;
	v_pk_mul_f32 v[188:189], v[208:209], s[44:45] op_sel_hi:[1,0]
	v_pk_mul_f32 v[186:187], v[210:211], s[44:45] op_sel_hi:[1,0]
	v_pk_mul_f32 v[166:167], v[212:213], s[44:45] op_sel_hi:[1,0]
	v_pk_mul_f32 v[168:169], v[214:215], s[44:45] op_sel_hi:[1,0]
	v_pk_mul_f32 v[190:191], v[216:217], s[44:45] op_sel_hi:[1,0]
	v_pk_fma_f32 v[36:37], v[188:189], v[150:151], v[166:167]
	v_pk_mul_f32 v[162:163], v[220:221], s[44:45] op_sel_hi:[1,0]
	v_pk_fma_f32 v[80:81], v[16:17], v[188:189], v[166:167]
	v_pk_fma_f32 v[16:17], v[16:17], v[190:191], v[36:37]
	v_pk_fma_f32 v[150:151], v[12:13], v[188:189], v[166:167]
	v_pk_fma_f32 v[36:37], v[12:13], v[190:191], v[80:81]
	v_pk_fma_f32 v[80:81], v[12:13], v[162:163], v[16:17]
	v_pk_fma_f32 v[12:13], v[188:189], v[178:179], v[166:167]
	v_pk_mul_f32 v[192:193], v[218:219], s[44:45] op_sel_hi:[1,0]
	v_pk_fma_f32 v[12:13], v[20:21], v[190:191], v[12:13]
	v_pk_fma_f32 v[38:39], v[186:187], v[174:175], v[168:169]
	v_pk_fma_f32 v[16:17], v[8:9], v[162:163], v[12:13]
	v_pk_fma_f32 v[12:13], v[20:21], v[188:189], v[166:167]
	v_pk_mul_f32 v[164:165], v[222:223], s[44:45] op_sel_hi:[1,0]
	v_pk_fma_f32 v[12:13], v[8:9], v[190:191], v[12:13]
	v_pk_fma_f32 v[8:9], v[8:9], v[188:189], v[166:167]
	v_pk_fma_f32 v[12:13], v[0:1], v[162:163], v[12:13]
	v_pk_fma_f32 v[8:9], v[0:1], v[190:191], v[8:9]
	v_pk_fma_f32 v[0:1], v[0:1], v[188:189], v[166:167]
	v_pk_fma_f32 v[8:9], v[4:5], v[162:163], v[8:9]
	v_pk_fma_f32 v[0:1], v[4:5], v[190:191], v[0:1]
	v_exp_f32_e64 v4, -v128
	v_exp_f32_e64 v5, -v129
	v_pk_fma_f32 v[82:83], v[18:19], v[186:187], v[168:169]
	v_pk_fma_f32 v[18:19], v[18:19], v[192:193], v[38:39]
	v_pk_fma_f32 v[174:175], v[14:15], v[186:187], v[168:169]
	v_pk_fma_f32 v[38:39], v[14:15], v[192:193], v[82:83]
	v_pk_fma_f32 v[82:83], v[14:15], v[164:165], v[18:19]
	v_pk_fma_f32 v[14:15], v[186:187], v[182:183], v[168:169]
	v_add_f32_e32 v4, 1.0, v4
	v_pk_fma_f32 v[14:15], v[22:23], v[192:193], v[14:15]
	v_rcp_f32_e32 v4, v4
	v_pk_fma_f32 v[18:19], v[10:11], v[164:165], v[14:15]
	v_pk_fma_f32 v[14:15], v[22:23], v[186:187], v[168:169]
	v_add_f32_e32 v5, 1.0, v5
	v_pk_fma_f32 v[14:15], v[10:11], v[192:193], v[14:15]
	v_pk_fma_f32 v[10:11], v[10:11], v[186:187], v[168:169]
	v_rcp_f32_e32 v5, v5
	v_pk_fma_f32 v[14:15], v[2:3], v[164:165], v[14:15]
	v_pk_fma_f32 v[10:11], v[2:3], v[192:193], v[10:11]
	v_pk_fma_f32 v[2:3], v[2:3], v[186:187], v[168:169]
	v_pk_fma_f32 v[194:195], v[28:29], v[188:189], v[166:167]
	v_pk_fma_f32 v[196:197], v[30:31], v[186:187], v[168:169]
	v_pk_fma_f32 v[10:11], v[6:7], v[164:165], v[10:11]
	v_pk_fma_f32 v[2:3], v[6:7], v[192:193], v[2:3]
	v_mul_f32_e32 v6, v128, v68
	v_pk_fma_f32 v[174:175], v[30:31], v[192:193], v[174:175]
	v_pk_fma_f32 v[150:151], v[28:29], v[190:191], v[150:151]
	v_pk_fma_f32 v[196:197], v[26:27], v[192:193], v[196:197]
	v_pk_fma_f32 v[194:195], v[24:25], v[190:191], v[194:195]
	v_mul_f32_e32 v4, v4, v6
	v_mul_f32_e32 v6, v129, v69
	v_pk_fma_f32 v[36:37], v[28:29], v[162:163], v[36:37]
	v_pk_fma_f32 v[38:39], v[30:31], v[164:165], v[38:39]
	v_pk_fma_f32 v[28:29], v[24:25], v[162:163], v[150:151]
	v_pk_fma_f32 v[30:31], v[26:27], v[164:165], v[174:175]
	v_pk_fma_f32 v[24:25], v[162:163], v[180:181], v[194:195]
	v_pk_fma_f32 v[26:27], v[164:165], v[184:185], v[196:197]
	v_pk_fma_f32 v[0:1], v[162:163], v[172:173], v[0:1]
	v_pk_fma_f32 v[2:3], v[164:165], v[176:177], v[2:3]
	v_exp_f32_e64 v7, -v130
	v_mul_f32_e32 v5, v5, v6
	v_cvt_pk_bf16_f32 v4, v4, v5
	v_exp_f32_e64 v5, -v131
	v_add_f32_e32 v6, 1.0, v7
	v_rcp_f32_e32 v6, v6
	v_mul_f32_e32 v7, v130, v70
	v_add_f32_e32 v5, 1.0, v5
	v_rcp_f32_e32 v5, v5
	v_mul_f32_e32 v6, v6, v7
	v_mul_f32_e32 v7, v131, v71
	v_exp_f32_e64 v21, -v132
	v_mul_f32_e32 v5, v5, v7
	v_cvt_pk_bf16_f32 v5, v6, v5
	v_exp_f32_e64 v6, -v133
	v_add_f32_e32 v7, 1.0, v21
	v_rcp_f32_e32 v7, v7
	v_mul_f32_e32 v21, v132, v80
	v_add_f32_e32 v6, 1.0, v6
	v_rcp_f32_e32 v6, v6
	v_mul_f32_e32 v7, v7, v21
	v_mul_f32_e32 v21, v133, v81
	v_exp_f32_e64 v22, -v134
	v_mul_f32_e32 v6, v6, v21
	v_exp_f32_e64 v21, -v135
	v_cvt_pk_bf16_f32 v6, v7, v6
	v_add_f32_e32 v7, 1.0, v22
	v_rcp_f32_e32 v7, v7
	v_add_f32_e32 v21, 1.0, v21
	v_rcp_f32_e32 v21, v21
	v_mul_f32_e32 v22, v134, v82
	v_lshl_or_b32 v20, s10, 7, v155
	v_mul_f32_e32 v7, v7, v22
	v_mul_f32_e32 v22, v135, v83
	v_mul_f32_e32 v21, v21, v22
	v_cvt_pk_bf16_f32 v7, v7, v21
	s_and_saveexec_b64 s[12:13], s[0:1]
	s_cbranch_execz .LBB0_809
	v_mov_b64_e32 v[22:23], s[18:19]
	v_mad_i64_i32 v[22:23], s[10:11], v20, s92, v[22:23]
	v_lshl_add_u64 v[22:23], v[148:149], 1, v[22:23]
	global_store_dwordx4 v[22:23], v[4:7], off
